# v61 + w1 hidden-activation epilogue stores without the nt hint (A/B of cache policy)
# speedup vs baseline: 1.0189x; 1.0189x over previous
; #define PG8_STAGE(bufoff, gbase, voff) do { _Pragma("unroll") for (int _i = 0; _i < 2; ++_i) \
;         __builtin_amdgcn_global_load_lds((const unsigned*)((const char*)(gbase) + (voff)[_i]), (LAS unsigned*)(lds + (bufoff) + ldsw + _i * 8192), 16, 0, 0); } while (0)
; #define PG8_LDA(dst, b, h) do { _Pragma("unroll") for (int m = 0; m < 4; ++m) _Pragma("unroll") for (int k = 0; k < 2; ++k) dst[m][k] = *(const LAS bf16x8*)(lds + PG8_SA(b, h) + aoff + m * 2048 + k * 1024); } while (0)
; #define PG8_LDB(dst, b, h) do { _Pragma("unroll") for (int n = 0; n < 2; ++n) _Pragma("unroll") for (int k = 0; k < 2; ++k) dst[n][k] = *(const LAS bf16x8*)(lds + PG8_SB(b, h) + boff + n * 2048 + k * 1024); } while (0)
; #define PG8_MMA(ai, bj, At, Bt) do { __builtin_amdgcn_s_setprio(1); _Pragma("unroll") for (int m = 0; m < 4; ++m) _Pragma("unroll") for (int n = 0; n < 2; ++n) _Pragma("unroll") for (int k = 0; k < 2; ++k) \
;         acc[ai][bj][m][n] = __builtin_amdgcn_mfma_f32_16x16x32_bf16(Bt[n][k], At[m][k], acc[ai][bj][m][n], 0, 0, 0); __builtin_amdgcn_s_setprio(0); } while (0)
; #define PG8_WAIT_V(n) asm volatile("s_waitcnt vmcnt(" #n ")" ::: "memory")
; #define PG8_WAIT_L(n) asm volatile("s_waitcnt lgkmcnt(" #n ")" ::: "memory")
; template <class Epi, class Sched>
; __device__ __forceinline__ void gemm_phase(LAS unsigned char* lds, const Gemm g, const Sched& S, const Epi& E) {
;     ...
;         for (int t = 0; t < nt; t += 2) {
;             const bool last = (t == nt - 2);
;             const char* a1 = cA + (size_t)(t + 1) * kstep;
;             const char* a2 = last ? nA : cA + (size_t)(t + 2) * kstep; const char* b2 = last ? nB : cB + (size_t)(t + 2) * kstep;
;             const char* a3 = a2 + kstep; const char* b3 = b2 + kstep;
;             PG8_LDB(B0, 0, 0); PG8_SCHED; PG8_LDA(At, 0, 0); PG8_STAGE(PG8_SA(1, 1), a1 + hstep, voffA);
;             PG8_WAIT_L(8); PG8_BAR; PG8_WAIT_L(0); PG8_MMA(0, 0, At, B0); PG8_BAR; PG8_SCHED;
;             PG8_LDB(B1, 0, 1); PG8_STAGE(PG8_SB(0, 0), b2, voffB);
;             PG8_BAR; PG8_WAIT_L(0); PG8_MMA(0, 1, At, B1); PG8_BAR;
;             PG8_LDA(At, 0, 1); PG8_STAGE(PG8_SA(0, 0), a2, voffA);
;             PG8_BAR; PG8_WAIT_L(0); PG8_MMA(1, 0, At, B0); PG8_BAR; PG8_SCHED;
;             PG8_STAGE(PG8_SB(0, 1), b2 + hstep, voffB);
;             PG8_WAIT_V(6); PG8_BAR; PG8_MMA(1, 1, At, B1); PG8_BAR;
.LBB0_73:
	s_add_u32 s38, s46, 0xfff80080
	s_addc_u32 s39, s47, -1
	s_cmp_eq_u32 s73, 28
	s_cselect_b32 s51, s29, s39
	s_cselect_b32 s50, s69, s38
	s_cselect_b32 s49, s27, s72
	s_cselect_b32 s48, s70, s71
	s_add_i32 m0, s9, 0xc000
	s_nop 0
	global_load_lds_dwordx4 v138, s[46:47]
	s_add_i32 m0, s9, 0xe000
	s_nop 0
	global_load_lds_dwordx4 v136, s[46:47]
	s_add_i32 s74, 0, 0x10000
	ds_read_b128 v[146:149], v226
	ds_read_b128 v[150:153], v226 offset:1024
	ds_read_b128 v[154:157], v226 offset:2048
	ds_read_b128 v[160:163], v226 offset:3072
	ds_read_b128 v[164:167], v145
	ds_read_b128 v[168:171], v145 offset:1024
	ds_read_b128 v[172:175], v145 offset:2048
	ds_read_b128 v[176:179], v145 offset:3072
	ds_read_b128 v[180:183], v145 offset:4096
	ds_read_b128 v[184:187], v145 offset:5120
	ds_read_b128 v[188:191], v145 offset:6144
	ds_read_b128 v[192:195], v145 offset:7168
	s_add_i32 s75, 0, 0x14000
	ds_read_b128 v[196:199], v226 offset:16384
	ds_read_b128 v[200:203], v226 offset:17408
	ds_read_b128 v[204:207], v226 offset:18432
	ds_read_b128 v[210:213], v226 offset:19456
	s_waitcnt lgkmcnt(4)
	s_barrier
	s_waitcnt lgkmcnt(0)
	v_mfma_f32_16x16x32_bf16 v[126:129], v[146:149], v[164:167], v[126:129]
	v_mfma_f32_16x16x32_bf16 v[122:125], v[154:157], v[164:167], v[122:125]
	v_mfma_f32_16x16x32_bf16 v[110:113], v[146:149], v[172:175], v[110:113]
	v_mfma_f32_16x16x32_bf16 v[106:109], v[154:157], v[172:175], v[106:109]
	v_mfma_f32_16x16x32_bf16 v[94:97], v[146:149], v[180:183], v[94:97]
	v_mfma_f32_16x16x32_bf16 v[90:93], v[154:157], v[180:183], v[90:93]
	v_mfma_f32_16x16x32_bf16 v[78:81], v[146:149], v[188:191], v[78:81]
	v_mfma_f32_16x16x32_bf16 v[74:77], v[154:157], v[188:191], v[74:77]
	v_mfma_f32_16x16x32_bf16 v[126:129], v[150:153], v[168:171], v[126:129]
	v_mfma_f32_16x16x32_bf16 v[122:125], v[160:163], v[168:171], v[122:125]
	v_mfma_f32_16x16x32_bf16 v[110:113], v[150:153], v[176:179], v[110:113]
	v_mfma_f32_16x16x32_bf16 v[106:109], v[160:163], v[176:179], v[106:109]
	v_mfma_f32_16x16x32_bf16 v[94:97], v[150:153], v[184:187], v[94:97]
	v_mfma_f32_16x16x32_bf16 v[90:93], v[160:163], v[184:187], v[90:93]
	v_mfma_f32_16x16x32_bf16 v[78:81], v[150:153], v[192:195], v[78:81]
	v_mfma_f32_16x16x32_bf16 v[74:77], v[160:163], v[192:195], v[74:77]
	v_mfma_f32_16x16x32_bf16 v[118:121], v[196:199], v[164:167], v[118:121]
	v_mfma_f32_16x16x32_bf16 v[114:117], v[204:207], v[164:167], v[114:117]
	v_mfma_f32_16x16x32_bf16 v[102:105], v[196:199], v[172:175], v[102:105]
	v_mfma_f32_16x16x32_bf16 v[98:101], v[204:207], v[172:175], v[98:101]
	v_mfma_f32_16x16x32_bf16 v[86:89], v[196:199], v[180:183], v[86:89]
	v_mfma_f32_16x16x32_bf16 v[82:85], v[204:207], v[180:183], v[82:85]
	v_mfma_f32_16x16x32_bf16 v[70:73], v[196:199], v[188:191], v[70:73]
	v_mfma_f32_16x16x32_bf16 v[66:69], v[204:207], v[188:191], v[66:69]
	v_mfma_f32_16x16x32_bf16 v[118:121], v[200:203], v[168:171], v[118:121]
	v_mfma_f32_16x16x32_bf16 v[114:117], v[210:213], v[168:171], v[114:117]
	v_mfma_f32_16x16x32_bf16 v[102:105], v[200:203], v[176:179], v[102:105]
	v_mfma_f32_16x16x32_bf16 v[98:101], v[210:213], v[176:179], v[98:101]
	v_mfma_f32_16x16x32_bf16 v[86:89], v[200:203], v[184:187], v[86:89]
	v_mfma_f32_16x16x32_bf16 v[82:85], v[210:213], v[184:187], v[82:85]
	v_mfma_f32_16x16x32_bf16 v[70:73], v[200:203], v[192:195], v[70:73]
	v_mfma_f32_16x16x32_bf16 v[66:69], v[210:213], v[192:195], v[66:69]
	s_barrier
	s_add_i32 s38, s74, s56
	s_mov_b32 m0, s38
	s_nop 0
	global_load_lds_dwordx4 v0, s[48:49]
	s_add_i32 m0, s38, 0x2000
	s_nop 0
	global_load_lds_dwordx4 v130, s[48:49]
	s_mov_b32 m0, s9
	s_nop 0
	global_load_lds_dwordx4 v134, s[50:51]
	s_mov_b32 m0, s60
	s_nop 0
	global_load_lds_dwordx4 v132, s[50:51]
	ds_read_b128 v[164:167], v145 offset:16384
	ds_read_b128 v[168:171], v145 offset:17408
	ds_read_b128 v[172:175], v145 offset:18432
	ds_read_b128 v[176:179], v145 offset:19456
	ds_read_b128 v[180:183], v145 offset:20480
	ds_read_b128 v[184:187], v145 offset:21504
	ds_read_b128 v[188:191], v145 offset:22528
	ds_read_b128 v[192:195], v145 offset:23552
	s_waitcnt vmcnt(4)
	s_waitcnt lgkmcnt(0)
	s_barrier
	v_mfma_f32_16x16x32_bf16 v[62:65], v[146:149], v[164:167], v[62:65]
	v_mfma_f32_16x16x32_bf16 v[58:61], v[154:157], v[164:167], v[58:61]
	v_mfma_f32_16x16x32_bf16 v[46:49], v[146:149], v[172:175], v[46:49]
	v_mfma_f32_16x16x32_bf16 v[42:45], v[154:157], v[172:175], v[42:45]
	v_mfma_f32_16x16x32_bf16 v[30:33], v[146:149], v[180:183], v[30:33]
	v_mfma_f32_16x16x32_bf16 v[26:29], v[154:157], v[180:183], v[26:29]
	v_mfma_f32_16x16x32_bf16 v[14:17], v[146:149], v[188:191], v[14:17]
	v_mfma_f32_16x16x32_bf16 v[10:13], v[154:157], v[188:191], v[10:13]
	v_mfma_f32_16x16x32_bf16 v[62:65], v[150:153], v[168:171], v[62:65]
	v_mfma_f32_16x16x32_bf16 v[58:61], v[160:163], v[168:171], v[58:61]
	v_mfma_f32_16x16x32_bf16 v[46:49], v[150:153], v[176:179], v[46:49]
	v_mfma_f32_16x16x32_bf16 v[42:45], v[160:163], v[176:179], v[42:45]
	v_mfma_f32_16x16x32_bf16 v[30:33], v[150:153], v[184:187], v[30:33]
	v_mfma_f32_16x16x32_bf16 v[26:29], v[160:163], v[184:187], v[26:29]
	v_mfma_f32_16x16x32_bf16 v[14:17], v[150:153], v[192:195], v[14:17]
	v_mfma_f32_16x16x32_bf16 v[10:13], v[160:163], v[192:195], v[10:13]
	v_mfma_f32_16x16x32_bf16 v[54:57], v[196:199], v[164:167], v[54:57]
	v_mfma_f32_16x16x32_bf16 v[50:53], v[204:207], v[164:167], v[50:53]
	v_mfma_f32_16x16x32_bf16 v[38:41], v[196:199], v[172:175], v[38:41]
	v_mfma_f32_16x16x32_bf16 v[34:37], v[204:207], v[172:175], v[34:37]
	v_mfma_f32_16x16x32_bf16 v[22:25], v[196:199], v[180:183], v[22:25]
	v_mfma_f32_16x16x32_bf16 v[18:21], v[204:207], v[180:183], v[18:21]
	v_mfma_f32_16x16x32_bf16 v[6:9], v[196:199], v[188:191], v[6:9]
	v_mfma_f32_16x16x32_bf16 v[2:5], v[204:207], v[188:191], v[2:5]
	v_mfma_f32_16x16x32_bf16 v[54:57], v[200:203], v[168:171], v[54:57]
	v_mfma_f32_16x16x32_bf16 v[50:53], v[210:213], v[168:171], v[50:53]
	v_mfma_f32_16x16x32_bf16 v[38:41], v[200:203], v[176:179], v[38:41]
	v_mfma_f32_16x16x32_bf16 v[34:37], v[210:213], v[176:179], v[34:37]
	v_mfma_f32_16x16x32_bf16 v[22:25], v[200:203], v[184:187], v[22:25]
	v_mfma_f32_16x16x32_bf16 v[18:21], v[210:213], v[184:187], v[18:21]
	v_mfma_f32_16x16x32_bf16 v[6:9], v[200:203], v[192:195], v[6:9]
	v_mfma_f32_16x16x32_bf16 v[2:5], v[210:213], v[192:195], v[2:5]
	s_barrier
; #define PG8_STAGE(bufoff, gbase, voff) do { _Pragma("unroll") for (int _i = 0; _i < 2; ++_i) \
;         __builtin_amdgcn_global_load_lds((const unsigned*)((const char*)(gbase) + (voff)[_i]), (LAS unsigned*)(lds + (bufoff) + ldsw + _i * 8192), 16, 0, 0); } while (0)
; #define PG8_LDA(dst, b, h) do { _Pragma("unroll") for (int m = 0; m < 4; ++m) _Pragma("unroll") for (int k = 0; k < 2; ++k) dst[m][k] = *(const LAS bf16x8*)(lds + PG8_SA(b, h) + aoff + m * 2048 + k * 1024); } while (0)
; #define PG8_LDB(dst, b, h) do { _Pragma("unroll") for (int n = 0; n < 2; ++n) _Pragma("unroll") for (int k = 0; k < 2; ++k) dst[n][k] = *(const LAS bf16x8*)(lds + PG8_SB(b, h) + boff + n * 2048 + k * 1024); } while (0)
; #define PG8_MMA(ai, bj, At, Bt) do { __builtin_amdgcn_s_setprio(1); _Pragma("unroll") for (int m = 0; m < 4; ++m) _Pragma("unroll") for (int n = 0; n < 2; ++n) _Pragma("unroll") for (int k = 0; k < 2; ++k) \
;         acc[ai][bj][m][n] = __builtin_amdgcn_mfma_f32_16x16x32_bf16(Bt[n][k], At[m][k], acc[ai][bj][m][n], 0, 0, 0); __builtin_amdgcn_s_setprio(0); } while (0)
; #define PG8_WAIT_V(n) asm volatile("s_waitcnt vmcnt(" #n ")" ::: "memory")
; #define PG8_WAIT_L(n) asm volatile("s_waitcnt lgkmcnt(" #n ")" ::: "memory")
; #define PG8_BAR __builtin_amdgcn_s_barrier()
; #define PG8_SCHED __builtin_amdgcn_sched_barrier(0)
; template <class Epi, class Sched>
; __device__ __forceinline__ void gemm_phase(LAS unsigned char* lds, const Gemm g, const Sched& S, const Epi& E) {
;     ...
;             PG8_LDB(B0, 1, 0); PG8_SCHED; PG8_LDA(At, 1, 0); PG8_STAGE(PG8_SA(0, 1), a2 + hstep, voffA);
;             PG8_WAIT_L(8); PG8_BAR; PG8_WAIT_L(0); PG8_MMA(0, 0, At, B0); PG8_BAR; PG8_SCHED;
;             PG8_LDB(B1, 1, 1); PG8_STAGE(PG8_SB(1, 0), b3, voffB);
;             PG8_BAR; PG8_WAIT_L(0); PG8_MMA(0, 1, At, B1); PG8_BAR;
;             PG8_LDA(At, 1, 1); PG8_STAGE(PG8_SA(1, 0), a3, voffA);
;             PG8_BAR; PG8_WAIT_L(0); PG8_MMA(1, 0, At, B0); PG8_BAR; PG8_SCHED;
;             PG8_STAGE(PG8_SB(1, 1), b3 + hstep, voffB);
;             PG8_WAIT_V(6); PG8_BAR; PG8_MMA(1, 1, At, B1); PG8_BAR;
;         }
	s_add_u32 s38, s48, 0x80000
	s_addc_u32 s39, s49, 0
	s_add_i32 s74, s75, s56
	s_mov_b32 m0, s74
	s_nop 0
	global_load_lds_dwordx4 v0, s[38:39]
	s_add_i32 m0, s74, 0x2000
	s_nop 0
	global_load_lds_dwordx4 v130, s[38:39]
	s_add_u32 s38, s50, 0x80000
	s_addc_u32 s39, s51, 0
	s_mov_b32 m0, s61
	s_nop 0
	global_load_lds_dwordx4 v134, s[38:39]
	s_mov_b32 m0, s62
	s_nop 0
	global_load_lds_dwordx4 v132, s[38:39]
	s_add_i32 s74, 0, 0x18000
	ds_read_b128 v[146:149], v226 offset:32768
	ds_read_b128 v[150:153], v226 offset:33792
	ds_read_b128 v[154:157], v226 offset:34816
	ds_read_b128 v[160:163], v226 offset:35840
	ds_read_b128 v[164:167], v145 offset:32768
	ds_read_b128 v[168:171], v145 offset:33792
	ds_read_b128 v[172:175], v145 offset:34816
	ds_read_b128 v[176:179], v145 offset:35840
	ds_read_b128 v[180:183], v145 offset:36864
	ds_read_b128 v[184:187], v145 offset:37888
	ds_read_b128 v[188:191], v145 offset:38912
	ds_read_b128 v[192:195], v145 offset:39936
	s_nop 0
	ds_read_b128 v[196:199], v226 offset:49152
	ds_read_b128 v[200:203], v226 offset:50176
	ds_read_b128 v[204:207], v226 offset:51200
	ds_read_b128 v[210:213], v226 offset:52224
	s_waitcnt lgkmcnt(4)
	s_barrier
	s_waitcnt lgkmcnt(0)
	v_mfma_f32_16x16x32_bf16 v[126:129], v[146:149], v[164:167], v[126:129]
	v_mfma_f32_16x16x32_bf16 v[122:125], v[154:157], v[164:167], v[122:125]
	v_mfma_f32_16x16x32_bf16 v[110:113], v[146:149], v[172:175], v[110:113]
	v_mfma_f32_16x16x32_bf16 v[106:109], v[154:157], v[172:175], v[106:109]
	v_mfma_f32_16x16x32_bf16 v[94:97], v[146:149], v[180:183], v[94:97]
	v_mfma_f32_16x16x32_bf16 v[90:93], v[154:157], v[180:183], v[90:93]
	v_mfma_f32_16x16x32_bf16 v[78:81], v[146:149], v[188:191], v[78:81]
	v_mfma_f32_16x16x32_bf16 v[74:77], v[154:157], v[188:191], v[74:77]
	v_mfma_f32_16x16x32_bf16 v[126:129], v[150:153], v[168:171], v[126:129]
	v_mfma_f32_16x16x32_bf16 v[122:125], v[160:163], v[168:171], v[122:125]
	v_mfma_f32_16x16x32_bf16 v[110:113], v[150:153], v[176:179], v[110:113]
	v_mfma_f32_16x16x32_bf16 v[106:109], v[160:163], v[176:179], v[106:109]
	v_mfma_f32_16x16x32_bf16 v[94:97], v[150:153], v[184:187], v[94:97]
	v_mfma_f32_16x16x32_bf16 v[90:93], v[160:163], v[184:187], v[90:93]
	v_mfma_f32_16x16x32_bf16 v[78:81], v[150:153], v[192:195], v[78:81]
	v_mfma_f32_16x16x32_bf16 v[74:77], v[160:163], v[192:195], v[74:77]
	v_mfma_f32_16x16x32_bf16 v[118:121], v[196:199], v[164:167], v[118:121]
	v_mfma_f32_16x16x32_bf16 v[114:117], v[204:207], v[164:167], v[114:117]
	v_mfma_f32_16x16x32_bf16 v[102:105], v[196:199], v[172:175], v[102:105]
	v_mfma_f32_16x16x32_bf16 v[98:101], v[204:207], v[172:175], v[98:101]
	v_mfma_f32_16x16x32_bf16 v[86:89], v[196:199], v[180:183], v[86:89]
	v_mfma_f32_16x16x32_bf16 v[82:85], v[204:207], v[180:183], v[82:85]
	v_mfma_f32_16x16x32_bf16 v[70:73], v[196:199], v[188:191], v[70:73]
	v_mfma_f32_16x16x32_bf16 v[66:69], v[204:207], v[188:191], v[66:69]
	v_mfma_f32_16x16x32_bf16 v[118:121], v[200:203], v[168:171], v[118:121]
	v_mfma_f32_16x16x32_bf16 v[114:117], v[210:213], v[168:171], v[114:117]
	v_mfma_f32_16x16x32_bf16 v[102:105], v[200:203], v[176:179], v[102:105]
	v_mfma_f32_16x16x32_bf16 v[98:101], v[210:213], v[176:179], v[98:101]
	v_mfma_f32_16x16x32_bf16 v[86:89], v[200:203], v[184:187], v[86:89]
	v_mfma_f32_16x16x32_bf16 v[82:85], v[210:213], v[184:187], v[82:85]
	v_mfma_f32_16x16x32_bf16 v[70:73], v[200:203], v[192:195], v[70:73]
	v_mfma_f32_16x16x32_bf16 v[66:69], v[210:213], v[192:195], v[66:69]
	s_barrier
	s_add_i32 s38, s74, s56
	s_add_u32 s100, s48, s36
	s_addc_u32 s101, s49, s37
	s_mov_b32 m0, s38
	s_nop 0
	global_load_lds_dwordx4 v0, s[100:101]
	s_add_i32 m0, s38, 0x2000
	s_nop 0
	global_load_lds_dwordx4 v130, s[100:101]
	s_mov_b32 m0, s64
	s_add_u32 s100, s50, s36
	s_addc_u32 s101, s51, s37
	global_load_lds_dwordx4 v134, s[100:101]
	s_mov_b32 m0, s65
	s_nop 0
	global_load_lds_dwordx4 v132, s[100:101]
	ds_read_b128 v[164:167], v145 offset:49152
	ds_read_b128 v[168:171], v145 offset:50176
	ds_read_b128 v[172:175], v145 offset:51200
	ds_read_b128 v[176:179], v145 offset:52224
	ds_read_b128 v[180:183], v145 offset:53248
	ds_read_b128 v[184:187], v145 offset:54272
	ds_read_b128 v[188:191], v145 offset:55296
	ds_read_b128 v[192:195], v145 offset:56320
	s_waitcnt vmcnt(4)
	s_waitcnt lgkmcnt(0)
	s_barrier
	v_mfma_f32_16x16x32_bf16 v[62:65], v[146:149], v[164:167], v[62:65]
	v_mfma_f32_16x16x32_bf16 v[58:61], v[154:157], v[164:167], v[58:61]
	v_mfma_f32_16x16x32_bf16 v[46:49], v[146:149], v[172:175], v[46:49]
	v_mfma_f32_16x16x32_bf16 v[42:45], v[154:157], v[172:175], v[42:45]
	v_mfma_f32_16x16x32_bf16 v[30:33], v[146:149], v[180:183], v[30:33]
	v_mfma_f32_16x16x32_bf16 v[26:29], v[154:157], v[180:183], v[26:29]
	v_mfma_f32_16x16x32_bf16 v[14:17], v[146:149], v[188:191], v[14:17]
	v_mfma_f32_16x16x32_bf16 v[10:13], v[154:157], v[188:191], v[10:13]
	v_mfma_f32_16x16x32_bf16 v[62:65], v[150:153], v[168:171], v[62:65]
	v_mfma_f32_16x16x32_bf16 v[58:61], v[160:163], v[168:171], v[58:61]
	v_mfma_f32_16x16x32_bf16 v[46:49], v[150:153], v[176:179], v[46:49]
	v_mfma_f32_16x16x32_bf16 v[42:45], v[160:163], v[176:179], v[42:45]
	v_mfma_f32_16x16x32_bf16 v[30:33], v[150:153], v[184:187], v[30:33]
	v_mfma_f32_16x16x32_bf16 v[26:29], v[160:163], v[184:187], v[26:29]
	v_mfma_f32_16x16x32_bf16 v[14:17], v[150:153], v[192:195], v[14:17]
	v_mfma_f32_16x16x32_bf16 v[10:13], v[160:163], v[192:195], v[10:13]
	s_add_u32 s38, s48, 0x80080
	s_addc_u32 s39, s49, 0
	s_add_i32 s48, s56, 0x1c000
	s_mov_b32 m0, s48
	s_nop 0
	global_load_lds_dwordx4 v0, s[38:39]
	s_add_i32 m0, s48, 0x2000
	s_nop 0
	global_load_lds_dwordx4 v130, s[38:39]
	v_mfma_f32_16x16x32_bf16 v[54:57], v[196:199], v[164:167], v[54:57]
	v_mfma_f32_16x16x32_bf16 v[50:53], v[204:207], v[164:167], v[50:53]
	v_mfma_f32_16x16x32_bf16 v[38:41], v[196:199], v[172:175], v[38:41]
	v_mfma_f32_16x16x32_bf16 v[34:37], v[204:207], v[172:175], v[34:37]
	v_mfma_f32_16x16x32_bf16 v[22:25], v[196:199], v[180:183], v[22:25]
	v_mfma_f32_16x16x32_bf16 v[18:21], v[204:207], v[180:183], v[18:21]
	v_mfma_f32_16x16x32_bf16 v[6:9], v[196:199], v[188:191], v[6:9]
	v_mfma_f32_16x16x32_bf16 v[2:5], v[204:207], v[188:191], v[2:5]
	v_mfma_f32_16x16x32_bf16 v[54:57], v[200:203], v[168:171], v[54:57]
	v_mfma_f32_16x16x32_bf16 v[50:53], v[210:213], v[168:171], v[50:53]
	v_mfma_f32_16x16x32_bf16 v[38:41], v[200:203], v[176:179], v[38:41]
	v_mfma_f32_16x16x32_bf16 v[34:37], v[210:213], v[176:179], v[34:37]
	v_mfma_f32_16x16x32_bf16 v[22:25], v[200:203], v[184:187], v[22:25]
	v_mfma_f32_16x16x32_bf16 v[18:21], v[210:213], v[184:187], v[18:21]
	v_mfma_f32_16x16x32_bf16 v[6:9], v[200:203], v[192:195], v[6:9]
	v_mfma_f32_16x16x32_bf16 v[2:5], v[210:213], v[192:195], v[2:5]
	s_add_i32 s73, s73, 2
	s_add_u32 s71, s71, 0x100
	s_addc_u32 s72, s72, 0
	s_add_u32 s46, s46, 0x100
	s_addc_u32 s47, s47, 0
	s_cmp_gt_u32 s73, 29
	s_barrier
; __device__ __forceinline__ unsigned cvt_pk_bf16(float lo, float hi) { unsigned r; asm("v_cvt_pk_bf16_f32 %0, %1, %2" : "=v"(r) : "v"(lo), "v"(hi)); return r; }
;     __device__ __forceinline__ void operator()(const f32x4 (&acc)[2][2][4][2], const Unit& u, int wr, int wc, int fr, int fq) const {
;         const int row0 = u.pm * BM + wr * 64 + fr, col0 = u.pn * BM + wc * 32 + 8 * fq;
; #pragma unroll
;         for (int ai = 0; ai < 2; ++ai)
; #pragma unroll
;             for (int m = 0; m < 4; ++m) { bf16_t* rowp = O + (size_t)(row0 + ai * HALF + m * 16) * ldc + col0;
; #pragma unroll
;                 for (int bj = 0; bj < 2; ++bj) { f32x4 v0 = acc[ai][bj][m][0], v1 = acc[ai][bj][m][1];
;                     if (ACT == 1) {
; #pragma unroll
;                         for (int j = 0; j < 4; ++j) { float a = fmaxf(v0[j], 0.f), b = fmaxf(v1[j], 0.f); v0[j] = a * a; v1[j] = b * b; } }
;                     u32x4 w; w.x = cvt_pk_bf16(v0[0], v0[1]); w.y = cvt_pk_bf16(v0[2], v0[3]); w.z = cvt_pk_bf16(v1[0], v1[1]); w.w = cvt_pk_bf16(v1[2], v1[3]);
;                     if (ACT == 1) __builtin_nontemporal_store(w, (u32x4*)(rowp + bj * HALF));
;                     else *(u32x4*)(rowp + bj * HALF) = w; } }
	s_cbranch_scc0 .LBB0_73
	v_lshl_add_u32 v146, s8, 8, v142
	v_max_f32_e32 v122, v122, v122
	v_ashrrev_i32_e32 v147, 31, v146
	v_max_f32_e32 v122, 0, v122
	v_max_f32_e32 v123, v123, v123
	v_max_f32_e32 v124, v124, v124
	v_lshl_or_b32 v140, s68, 8, v144
	v_lshlrev_b64 v[148:149], 14, v[146:147]
	v_mul_f32_e32 v147, v122, v122
	v_max_f32_e32 v122, v127, v127
	v_max_f32_e32 v123, 0, v123
	v_max_f32_e32 v124, 0, v124
	v_ashrrev_i32_e32 v141, 31, v140
	v_max_f32_e32 v126, v126, v126
	v_max_f32_e32 v122, 0, v122
	v_mul_f32_e32 v127, v123, v123
	v_max_f32_e32 v123, v128, v128
	v_mul_f32_e32 v128, v124, v124
	v_max_f32_e32 v124, v129, v129
	v_max_f32_e32 v125, v125, v125
	v_lshl_add_u64 v[148:149], s[24:25], 0, v[148:149]
	v_lshlrev_b64 v[150:151], 1, v[140:141]
	v_max_f32_e32 v126, 0, v126
	v_mul_f32_e32 v122, v122, v122
	v_max_f32_e32 v123, 0, v123
	v_max_f32_e32 v124, 0, v124
	v_max_f32_e32 v125, 0, v125
	v_max_f32_e32 v114, v114, v114
	v_lshl_add_u64 v[140:141], v[148:149], 0, v[150:151]
	v_mul_f32_e32 v126, v126, v126
	v_mul_f32_e32 v123, v123, v123
	v_mul_f32_e32 v124, v124, v124
	v_mul_f32_e32 v125, v125, v125
	v_cvt_pk_bf16_f32 v122, v126, v122
	v_max_f32_e32 v114, 0, v114
	v_max_f32_e32 v115, v115, v115
	v_max_f32_e32 v116, v116, v116
	v_cvt_pk_bf16_f32 v123, v123, v124
	v_cvt_pk_bf16_f32 v124, v147, v127
	v_cvt_pk_bf16_f32 v125, v128, v125
	global_store_dwordx4 v[140:141], v[122:125], off
	v_max_f32_e32 v115, 0, v115
	v_max_f32_e32 v116, 0, v116
	v_mul_f32_e32 v122, v114, v114
	v_max_f32_e32 v114, v119, v119
	v_max_f32_e32 v118, v118, v118
	v_max_f32_e32 v114, 0, v114
	v_mul_f32_e32 v119, v115, v115
	v_max_f32_e32 v115, v120, v120
	v_mul_f32_e32 v120, v116, v116
	v_max_f32_e32 v116, v121, v121
	v_max_f32_e32 v117, v117, v117
	v_max_f32_e32 v118, 0, v118
	v_mul_f32_e32 v114, v114, v114
	v_max_f32_e32 v115, 0, v115
	v_max_f32_e32 v116, 0, v116
	v_max_f32_e32 v117, 0, v117
	v_mul_f32_e32 v118, v118, v118
	v_mul_f32_e32 v115, v115, v115
	v_mul_f32_e32 v116, v116, v116
	v_mul_f32_e32 v117, v117, v117
	v_cvt_pk_bf16_f32 v114, v118, v114
	v_max_f32_e32 v106, v106, v106
	v_cvt_pk_bf16_f32 v115, v115, v116
	v_cvt_pk_bf16_f32 v116, v122, v119
	v_cvt_pk_bf16_f32 v117, v120, v117
	global_store_dwordx4 v[140:141], v[114:117], off offset:256
	v_max_f32_e32 v106, 0, v106
	v_max_f32_e32 v107, v107, v107
	v_or_b32_e32 v114, 16, v146
	v_max_f32_e32 v108, v108, v108
	v_ashrrev_i32_e32 v115, 31, v114
	v_mul_f32_e32 v116, v106, v106
	v_max_f32_e32 v106, v111, v111
	v_max_f32_e32 v107, 0, v107
	v_max_f32_e32 v108, 0, v108
	v_lshlrev_b64 v[114:115], 14, v[114:115]
	v_max_f32_e32 v110, v110, v110
	v_max_f32_e32 v106, 0, v106
	v_mul_f32_e32 v111, v107, v107
	v_max_f32_e32 v107, v112, v112
	v_mul_f32_e32 v112, v108, v108
	v_max_f32_e32 v108, v113, v113
	v_max_f32_e32 v109, v109, v109
	v_lshl_add_u64 v[114:115], s[24:25], 0, v[114:115]
	v_max_f32_e32 v110, 0, v110
	v_mul_f32_e32 v106, v106, v106
	v_max_f32_e32 v107, 0, v107
	v_max_f32_e32 v108, 0, v108
	v_max_f32_e32 v109, 0, v109
	v_max_f32_e32 v98, v98, v98
	v_lshl_add_u64 v[114:115], v[114:115], 0, v[150:151]
	v_mul_f32_e32 v110, v110, v110
	v_mul_f32_e32 v107, v107, v107
	v_mul_f32_e32 v108, v108, v108
	v_mul_f32_e32 v109, v109, v109
	v_cvt_pk_bf16_f32 v106, v110, v106
	v_max_f32_e32 v98, 0, v98
	v_max_f32_e32 v99, v99, v99
	v_max_f32_e32 v100, v100, v100
	v_cvt_pk_bf16_f32 v107, v107, v108
	v_cvt_pk_bf16_f32 v108, v116, v111
	v_cvt_pk_bf16_f32 v109, v112, v109
	global_store_dwordx4 v[114:115], v[106:109], off
	v_max_f32_e32 v99, 0, v99
	v_max_f32_e32 v100, 0, v100
	v_mul_f32_e32 v106, v98, v98
	v_max_f32_e32 v98, v103, v103
	v_max_f32_e32 v102, v102, v102
	v_max_f32_e32 v98, 0, v98
	v_mul_f32_e32 v103, v99, v99
	v_max_f32_e32 v99, v104, v104
	v_mul_f32_e32 v104, v100, v100
	v_max_f32_e32 v100, v105, v105
	v_max_f32_e32 v101, v101, v101
	v_max_f32_e32 v102, 0, v102
	v_mul_f32_e32 v98, v98, v98
	v_max_f32_e32 v99, 0, v99
	v_max_f32_e32 v100, 0, v100
	v_max_f32_e32 v101, 0, v101
	v_mul_f32_e32 v102, v102, v102
	v_mul_f32_e32 v99, v99, v99
	v_mul_f32_e32 v100, v100, v100
	v_mul_f32_e32 v101, v101, v101
	v_cvt_pk_bf16_f32 v98, v102, v98
	v_max_f32_e32 v90, v90, v90
	v_cvt_pk_bf16_f32 v99, v99, v100
	v_cvt_pk_bf16_f32 v100, v106, v103
	v_cvt_pk_bf16_f32 v101, v104, v101
	global_store_dwordx4 v[114:115], v[98:101], off offset:256
	v_max_f32_e32 v90, 0, v90
	v_max_f32_e32 v91, v91, v91
	v_or_b32_e32 v98, 32, v146
	v_max_f32_e32 v92, v92, v92
	v_ashrrev_i32_e32 v99, 31, v98
	v_mul_f32_e32 v100, v90, v90
	v_max_f32_e32 v90, v95, v95
	v_max_f32_e32 v91, 0, v91
	v_max_f32_e32 v92, 0, v92
	v_lshlrev_b64 v[98:99], 14, v[98:99]
	v_max_f32_e32 v94, v94, v94
	v_max_f32_e32 v90, 0, v90
	v_mul_f32_e32 v95, v91, v91
	v_max_f32_e32 v91, v96, v96
	v_mul_f32_e32 v96, v92, v92
	v_max_f32_e32 v92, v97, v97
	v_max_f32_e32 v93, v93, v93
	v_lshl_add_u64 v[98:99], s[24:25], 0, v[98:99]
	v_max_f32_e32 v94, 0, v94
	v_mul_f32_e32 v90, v90, v90
	v_max_f32_e32 v91, 0, v91
	v_max_f32_e32 v92, 0, v92
	v_max_f32_e32 v93, 0, v93
	v_max_f32_e32 v82, v82, v82
	v_lshl_add_u64 v[98:99], v[98:99], 0, v[150:151]
	v_mul_f32_e32 v94, v94, v94
	v_mul_f32_e32 v91, v91, v91
	v_mul_f32_e32 v92, v92, v92
	v_mul_f32_e32 v93, v93, v93
	v_cvt_pk_bf16_f32 v90, v94, v90
	v_max_f32_e32 v82, 0, v82
	v_max_f32_e32 v83, v83, v83
	v_max_f32_e32 v84, v84, v84
	v_cvt_pk_bf16_f32 v91, v91, v92
	v_cvt_pk_bf16_f32 v92, v100, v95
	v_cvt_pk_bf16_f32 v93, v96, v93
	global_store_dwordx4 v[98:99], v[90:93], off
	v_max_f32_e32 v83, 0, v83
	v_max_f32_e32 v84, 0, v84
	v_mul_f32_e32 v90, v82, v82
	v_max_f32_e32 v82, v87, v87
	v_max_f32_e32 v86, v86, v86
	v_max_f32_e32 v82, 0, v82
; __device__ __forceinline__ unsigned cvt_pk_bf16(float lo, float hi) { unsigned r; asm("v_cvt_pk_bf16_f32 %0, %1, %2" : "=v"(r) : "v"(lo), "v"(hi)); return r; }
;     __device__ __forceinline__ void operator()(const f32x4 (&acc)[2][2][4][2], const Unit& u, int wr, int wc, int fr, int fq) const {
;     ...
;         for (int ai = 0; ai < 2; ++ai)
; #pragma unroll
;             for (int m = 0; m < 4; ++m) { bf16_t* rowp = O + (size_t)(row0 + ai * HALF + m * 16) * ldc + col0;
; #pragma unroll
;                 for (int bj = 0; bj < 2; ++bj) { f32x4 v0 = acc[ai][bj][m][0], v1 = acc[ai][bj][m][1];
;                     if (ACT == 1) {
; #pragma unroll
;                         for (int j = 0; j < 4; ++j) { float a = fmaxf(v0[j], 0.f), b = fmaxf(v1[j], 0.f); v0[j] = a * a; v1[j] = b * b; } }
;                     u32x4 w; w.x = cvt_pk_bf16(v0[0], v0[1]); w.y = cvt_pk_bf16(v0[2], v0[3]); w.z = cvt_pk_bf16(v1[0], v1[1]); w.w = cvt_pk_bf16(v1[2], v1[3]);
;                     if (ACT == 1) __builtin_nontemporal_store(w, (u32x4*)(rowp + bj * HALF));
;                     else *(u32x4*)(rowp + bj * HALF) = w; } }
	v_mul_f32_e32 v87, v83, v83
	v_max_f32_e32 v83, v88, v88
	v_mul_f32_e32 v88, v84, v84
	v_max_f32_e32 v84, v89, v89
	v_max_f32_e32 v85, v85, v85
	v_max_f32_e32 v86, 0, v86
	v_mul_f32_e32 v82, v82, v82
	v_max_f32_e32 v83, 0, v83
	v_max_f32_e32 v84, 0, v84
	v_max_f32_e32 v85, 0, v85
	v_mul_f32_e32 v86, v86, v86
	v_mul_f32_e32 v83, v83, v83
	v_mul_f32_e32 v84, v84, v84
	v_mul_f32_e32 v85, v85, v85
	v_cvt_pk_bf16_f32 v82, v86, v82
	v_max_f32_e32 v74, v74, v74
	v_cvt_pk_bf16_f32 v83, v83, v84
	v_cvt_pk_bf16_f32 v84, v90, v87
	v_cvt_pk_bf16_f32 v85, v88, v85
	global_store_dwordx4 v[98:99], v[82:85], off offset:256
	v_max_f32_e32 v74, 0, v74
	v_max_f32_e32 v75, v75, v75
	v_or_b32_e32 v82, 48, v146
	v_max_f32_e32 v76, v76, v76
	v_ashrrev_i32_e32 v83, 31, v82
	v_mul_f32_e32 v84, v74, v74
	v_max_f32_e32 v74, v79, v79
	v_max_f32_e32 v75, 0, v75
	v_max_f32_e32 v76, 0, v76
	v_lshlrev_b64 v[82:83], 14, v[82:83]
	v_max_f32_e32 v78, v78, v78
	v_max_f32_e32 v74, 0, v74
	v_mul_f32_e32 v79, v75, v75
	v_max_f32_e32 v75, v80, v80
	v_mul_f32_e32 v80, v76, v76
	v_max_f32_e32 v76, v81, v81
	v_max_f32_e32 v77, v77, v77
	v_lshl_add_u64 v[82:83], s[24:25], 0, v[82:83]
	v_max_f32_e32 v78, 0, v78
	v_mul_f32_e32 v74, v74, v74
	v_max_f32_e32 v75, 0, v75
	v_max_f32_e32 v76, 0, v76
	v_max_f32_e32 v77, 0, v77
	v_max_f32_e32 v66, v66, v66
	v_max_f32_e32 v67, v67, v67
	v_max_f32_e32 v68, v68, v68
	v_lshl_add_u64 v[82:83], v[82:83], 0, v[150:151]
	v_mul_f32_e32 v78, v78, v78
	v_mul_f32_e32 v75, v75, v75
	v_mul_f32_e32 v76, v76, v76
	v_mul_f32_e32 v77, v77, v77
	v_cvt_pk_bf16_f32 v74, v78, v74
	v_max_f32_e32 v66, 0, v66
	v_max_f32_e32 v67, 0, v67
	v_max_f32_e32 v68, 0, v68
	v_cvt_pk_bf16_f32 v75, v75, v76
	v_cvt_pk_bf16_f32 v76, v84, v79
	v_cvt_pk_bf16_f32 v77, v80, v77
	global_store_dwordx4 v[82:83], v[74:77], off
	v_max_f32_e32 v69, v69, v69
	v_max_f32_e32 v70, v70, v70
	v_mul_f32_e32 v74, v66, v66
	v_max_f32_e32 v66, v71, v71
	v_mul_f32_e32 v71, v67, v67
	v_max_f32_e32 v67, v72, v72
	v_mul_f32_e32 v72, v68, v68
	v_max_f32_e32 v68, v73, v73
	v_max_f32_e32 v67, 0, v67
	v_max_f32_e32 v68, 0, v68
	v_max_f32_e32 v66, 0, v66
	v_mul_f32_e32 v67, v67, v67
	v_max_f32_e32 v69, 0, v69
	v_mul_f32_e32 v68, v68, v68
	v_max_f32_e32 v58, v58, v58
	v_max_f32_e32 v70, 0, v70
	v_mul_f32_e32 v66, v66, v66
	v_mul_f32_e32 v69, v69, v69
	v_cvt_pk_bf16_f32 v67, v67, v68
	v_cvt_pk_bf16_f32 v68, v74, v71
	v_max_f32_e32 v58, 0, v58
	v_max_f32_e32 v59, v59, v59
	v_max_f32_e32 v60, v60, v60
	v_mul_f32_e32 v70, v70, v70
	v_cvt_pk_bf16_f32 v66, v70, v66
	v_cvt_pk_bf16_f32 v69, v72, v69
	global_store_dwordx4 v[82:83], v[66:69], off offset:256
	v_max_f32_e32 v62, v62, v62
	v_max_f32_e32 v59, 0, v59
	v_mul_f32_e32 v68, v58, v58
	v_max_f32_e32 v58, v63, v63
	v_max_f32_e32 v60, 0, v60
	v_max_f32_e32 v62, 0, v62
	v_max_f32_e32 v58, 0, v58
	v_mul_f32_e32 v63, v59, v59
	v_max_f32_e32 v59, v64, v64
	v_mul_f32_e32 v64, v60, v60
	v_max_f32_e32 v60, v65, v65
	v_mul_f32_e32 v62, v62, v62
	v_mul_f32_e32 v58, v58, v58
	v_max_f32_e32 v59, 0, v59
	v_max_f32_e32 v60, 0, v60
	v_max_f32_e32 v61, v61, v61
	s_mov_b32 s8, 0x200000
	v_mul_f32_e32 v59, v59, v59
	v_max_f32_e32 v61, 0, v61
	v_mul_f32_e32 v60, v60, v60
	v_cvt_pk_bf16_f32 v58, v62, v58
	v_add_co_u32_e32 v62, vcc, s8, v140
	v_max_f32_e32 v50, v50, v50
	v_max_f32_e32 v51, v51, v51
	v_max_f32_e32 v52, v52, v52
	v_mul_f32_e32 v61, v61, v61
	v_cvt_pk_bf16_f32 v59, v59, v60
	v_cvt_pk_bf16_f32 v60, v68, v63
	v_addc_co_u32_e32 v63, vcc, 0, v141, vcc
	v_max_f32_e32 v50, 0, v50
	v_max_f32_e32 v51, 0, v51
	v_max_f32_e32 v52, 0, v52
	v_cvt_pk_bf16_f32 v61, v64, v61
	global_store_dwordx4 v[62:63], v[58:61], off
	v_max_f32_e32 v53, v53, v53
	s_mov_b64 s[38:39], 0x200000
	v_mul_f32_e32 v58, v50, v50
	v_max_f32_e32 v50, v55, v55
	v_mul_f32_e32 v55, v51, v51
	v_max_f32_e32 v51, v56, v56
	v_mul_f32_e32 v56, v52, v52
	v_max_f32_e32 v52, v57, v57
	v_max_f32_e32 v51, 0, v51
	v_max_f32_e32 v52, 0, v52
	v_max_f32_e32 v54, v54, v54
	v_max_f32_e32 v50, 0, v50
	v_mul_f32_e32 v51, v51, v51
	v_max_f32_e32 v53, 0, v53
	v_mul_f32_e32 v52, v52, v52
	v_max_f32_e32 v42, v42, v42
	v_lshl_add_u64 v[66:67], v[140:141], 0, s[38:39]
	v_max_f32_e32 v54, 0, v54
	v_mul_f32_e32 v50, v50, v50
	v_mul_f32_e32 v53, v53, v53
	v_cvt_pk_bf16_f32 v51, v51, v52
	v_cvt_pk_bf16_f32 v52, v58, v55
	v_max_f32_e32 v42, 0, v42
	v_max_f32_e32 v43, v43, v43
	v_max_f32_e32 v44, v44, v44
	v_mul_f32_e32 v54, v54, v54
	v_cvt_pk_bf16_f32 v50, v54, v50
	v_cvt_pk_bf16_f32 v53, v56, v53
	global_store_dwordx4 v[66:67], v[50:53], off offset:256
	v_max_f32_e32 v46, v46, v46
	v_max_f32_e32 v43, 0, v43
	v_mul_f32_e32 v52, v42, v42
	v_max_f32_e32 v42, v47, v47
	v_max_f32_e32 v44, 0, v44
	v_max_f32_e32 v46, 0, v46
	v_max_f32_e32 v42, 0, v42
	v_mul_f32_e32 v47, v43, v43
	v_max_f32_e32 v43, v48, v48
	v_mul_f32_e32 v48, v44, v44
	v_max_f32_e32 v44, v49, v49
	v_mul_f32_e32 v46, v46, v46
	v_mul_f32_e32 v42, v42, v42
	v_max_f32_e32 v43, 0, v43
	v_max_f32_e32 v44, 0, v44
	v_max_f32_e32 v45, v45, v45
	s_mov_b32 s8, 0x240000
	v_mul_f32_e32 v43, v43, v43
	v_max_f32_e32 v45, 0, v45
	v_mul_f32_e32 v44, v44, v44
	v_cvt_pk_bf16_f32 v42, v46, v42
	v_add_co_u32_e32 v46, vcc, s8, v140
; __device__ __forceinline__ unsigned cvt_pk_bf16(float lo, float hi) { unsigned r; asm("v_cvt_pk_bf16_f32 %0, %1, %2" : "=v"(r) : "v"(lo), "v"(hi)); return r; }
;     __device__ __forceinline__ void operator()(const f32x4 (&acc)[2][2][4][2], const Unit& u, int wr, int wc, int fr, int fq) const {
;     ...
;         for (int ai = 0; ai < 2; ++ai)
; #pragma unroll
;             for (int m = 0; m < 4; ++m) { bf16_t* rowp = O + (size_t)(row0 + ai * HALF + m * 16) * ldc + col0;
; #pragma unroll
;                 for (int bj = 0; bj < 2; ++bj) { f32x4 v0 = acc[ai][bj][m][0], v1 = acc[ai][bj][m][1];
;                     if (ACT == 1) {
; #pragma unroll
;                         for (int j = 0; j < 4; ++j) { float a = fmaxf(v0[j], 0.f), b = fmaxf(v1[j], 0.f); v0[j] = a * a; v1[j] = b * b; } }
;                     u32x4 w; w.x = cvt_pk_bf16(v0[0], v0[1]); w.y = cvt_pk_bf16(v0[2], v0[3]); w.z = cvt_pk_bf16(v1[0], v1[1]); w.w = cvt_pk_bf16(v1[2], v1[3]);
;                     if (ACT == 1) __builtin_nontemporal_store(w, (u32x4*)(rowp + bj * HALF));
;                     else *(u32x4*)(rowp + bj * HALF) = w; } }
	v_max_f32_e32 v34, v34, v34
	v_max_f32_e32 v35, v35, v35
	v_max_f32_e32 v36, v36, v36
	v_mul_f32_e32 v45, v45, v45
	v_cvt_pk_bf16_f32 v43, v43, v44
	v_cvt_pk_bf16_f32 v44, v52, v47
	v_addc_co_u32_e32 v47, vcc, 0, v141, vcc
	v_max_f32_e32 v34, 0, v34
	v_max_f32_e32 v35, 0, v35
	v_max_f32_e32 v36, 0, v36
	v_cvt_pk_bf16_f32 v45, v48, v45
	global_store_dwordx4 v[46:47], v[42:45], off
	v_max_f32_e32 v37, v37, v37
	s_mov_b64 s[38:39], 0x240000
	v_mul_f32_e32 v42, v34, v34
	v_max_f32_e32 v34, v39, v39
	v_mul_f32_e32 v39, v35, v35
	v_max_f32_e32 v35, v40, v40
	v_mul_f32_e32 v40, v36, v36
	v_max_f32_e32 v36, v41, v41
	v_max_f32_e32 v35, 0, v35
	v_max_f32_e32 v36, 0, v36
	v_max_f32_e32 v38, v38, v38
	v_max_f32_e32 v34, 0, v34
	v_mul_f32_e32 v35, v35, v35
	v_max_f32_e32 v37, 0, v37
	v_mul_f32_e32 v36, v36, v36
	v_max_f32_e32 v26, v26, v26
	v_lshl_add_u64 v[50:51], v[140:141], 0, s[38:39]
	v_max_f32_e32 v38, 0, v38
	v_mul_f32_e32 v34, v34, v34
	v_mul_f32_e32 v37, v37, v37
	v_cvt_pk_bf16_f32 v35, v35, v36
	v_cvt_pk_bf16_f32 v36, v42, v39
	v_max_f32_e32 v26, 0, v26
	v_max_f32_e32 v27, v27, v27
	v_max_f32_e32 v28, v28, v28
	v_mul_f32_e32 v38, v38, v38
	v_cvt_pk_bf16_f32 v34, v38, v34
	v_cvt_pk_bf16_f32 v37, v40, v37
	global_store_dwordx4 v[50:51], v[34:37], off offset:256
	v_max_f32_e32 v30, v30, v30
	v_max_f32_e32 v27, 0, v27
	v_mul_f32_e32 v36, v26, v26
	v_max_f32_e32 v26, v31, v31
	v_max_f32_e32 v28, 0, v28
	v_max_f32_e32 v30, 0, v30
	v_max_f32_e32 v26, 0, v26
	v_mul_f32_e32 v31, v27, v27
	v_max_f32_e32 v27, v32, v32
	v_mul_f32_e32 v32, v28, v28
	v_max_f32_e32 v28, v33, v33
	v_mul_f32_e32 v30, v30, v30
	v_mul_f32_e32 v26, v26, v26
	v_max_f32_e32 v27, 0, v27
	v_max_f32_e32 v28, 0, v28
	v_max_f32_e32 v29, v29, v29
	s_mov_b32 s8, 0x280000
	v_mul_f32_e32 v27, v27, v27
	v_max_f32_e32 v29, 0, v29
	v_mul_f32_e32 v28, v28, v28
	v_cvt_pk_bf16_f32 v26, v30, v26
	v_add_co_u32_e32 v30, vcc, s8, v140
	v_max_f32_e32 v18, v18, v18
	v_max_f32_e32 v19, v19, v19
	v_max_f32_e32 v20, v20, v20
	v_mul_f32_e32 v29, v29, v29
	v_cvt_pk_bf16_f32 v27, v27, v28
	v_cvt_pk_bf16_f32 v28, v36, v31
	v_addc_co_u32_e32 v31, vcc, 0, v141, vcc
	v_max_f32_e32 v18, 0, v18
	v_max_f32_e32 v19, 0, v19
	v_max_f32_e32 v20, 0, v20
	v_cvt_pk_bf16_f32 v29, v32, v29
	global_store_dwordx4 v[30:31], v[26:29], off
	v_max_f32_e32 v21, v21, v21
	s_mov_b64 s[38:39], 0x280000
	v_mul_f32_e32 v26, v18, v18
	v_max_f32_e32 v18, v23, v23
	v_mul_f32_e32 v23, v19, v19
	v_max_f32_e32 v19, v24, v24
	v_mul_f32_e32 v24, v20, v20
	v_max_f32_e32 v20, v25, v25
	v_max_f32_e32 v19, 0, v19
	v_max_f32_e32 v20, 0, v20
	v_max_f32_e32 v22, v22, v22
	v_max_f32_e32 v18, 0, v18
	v_mul_f32_e32 v19, v19, v19
	v_max_f32_e32 v21, 0, v21
	v_mul_f32_e32 v20, v20, v20
	v_max_f32_e32 v10, v10, v10
	v_lshl_add_u64 v[34:35], v[140:141], 0, s[38:39]
	v_max_f32_e32 v22, 0, v22
	v_mul_f32_e32 v18, v18, v18
	v_mul_f32_e32 v21, v21, v21
	v_cvt_pk_bf16_f32 v19, v19, v20
	v_cvt_pk_bf16_f32 v20, v26, v23
	v_max_f32_e32 v10, 0, v10
	v_max_f32_e32 v11, v11, v11
	v_max_f32_e32 v12, v12, v12
	v_mul_f32_e32 v22, v22, v22
	v_cvt_pk_bf16_f32 v18, v22, v18
	v_cvt_pk_bf16_f32 v21, v24, v21
	global_store_dwordx4 v[34:35], v[18:21], off offset:256
	v_max_f32_e32 v14, v14, v14
	v_max_f32_e32 v11, 0, v11
	v_mul_f32_e32 v20, v10, v10
	v_max_f32_e32 v10, v15, v15
	v_max_f32_e32 v12, 0, v12
	v_max_f32_e32 v14, 0, v14
	v_max_f32_e32 v10, 0, v10
	v_mul_f32_e32 v15, v11, v11
	v_max_f32_e32 v11, v16, v16
	v_mul_f32_e32 v16, v12, v12
	v_max_f32_e32 v12, v17, v17
	v_mul_f32_e32 v14, v14, v14
	v_mul_f32_e32 v10, v10, v10
	v_max_f32_e32 v11, 0, v11
	v_max_f32_e32 v12, 0, v12
	v_max_f32_e32 v13, v13, v13
	s_mov_b32 s8, 0x2c0000
	v_mul_f32_e32 v11, v11, v11
	v_max_f32_e32 v13, 0, v13
	v_mul_f32_e32 v12, v12, v12
	v_cvt_pk_bf16_f32 v10, v14, v10
	v_add_co_u32_e32 v14, vcc, s8, v140
	v_max_f32_e32 v2, v2, v2
	v_max_f32_e32 v3, v3, v3
	v_max_f32_e32 v4, v4, v4
	v_mul_f32_e32 v13, v13, v13
	v_cvt_pk_bf16_f32 v11, v11, v12
	v_cvt_pk_bf16_f32 v12, v20, v15
	v_addc_co_u32_e32 v15, vcc, 0, v141, vcc
	v_max_f32_e32 v2, 0, v2
	v_max_f32_e32 v3, 0, v3
	v_max_f32_e32 v4, 0, v4
	v_cvt_pk_bf16_f32 v13, v16, v13
	global_store_dwordx4 v[14:15], v[10:13], off
	v_max_f32_e32 v5, v5, v5
	s_mov_b64 s[38:39], 0x2c0000
	v_mul_f32_e32 v10, v2, v2
	v_max_f32_e32 v2, v7, v7
	v_mul_f32_e32 v7, v3, v3
	v_max_f32_e32 v3, v8, v8
	v_mul_f32_e32 v8, v4, v4
	v_max_f32_e32 v4, v9, v9
	v_max_f32_e32 v6, v6, v6
	v_max_f32_e32 v2, 0, v2
	v_max_f32_e32 v3, 0, v3
	v_max_f32_e32 v4, 0, v4
	v_max_f32_e32 v5, 0, v5
	v_lshl_add_u64 v[18:19], v[140:141], 0, s[38:39]
	v_max_f32_e32 v6, 0, v6
	v_mul_f32_e32 v2, v2, v2
	v_mul_f32_e32 v3, v3, v3
	v_mul_f32_e32 v4, v4, v4
	v_mul_f32_e32 v5, v5, v5
	s_and_b64 vcc, exec, s[40:41]
	s_mov_b32 s68, s26
	s_mov_b32 s8, s28
	s_mov_b64 s[46:47], s[44:45]
	s_mov_b64 s[48:49], s[42:43]
	v_mul_f32_e32 v6, v6, v6
	v_cvt_pk_bf16_f32 v2, v6, v2
	v_cvt_pk_bf16_f32 v3, v3, v4
	v_cvt_pk_bf16_f32 v4, v10, v7
	v_cvt_pk_bf16_f32 v5, v8, v5
	global_store_dwordx4 v[18:19], v[2:5], off offset:256
	s_cbranch_vccz .LBB0_70
	s_waitcnt vmcnt(0)
	s_cmpk_gt_u32 s52, 0xff
	s_cbranch_scc1 .LBB0_77
	s_barrier
